# v11 + K-loop load segments: LDS fragment reads issued first, scalar pointer updates / address adds / m0 set-up moved behind them
# baseline (speedup 1.0000x reference)
.LBB0_344:
	v_add_u32_e32 v17, 0x10000, v237
	ds_read_b128 v[134:137], v17
	ds_read_b128 v[138:141], v17 offset:1024
	ds_read_b128 v[142:145], v17 offset:2048
	ds_read_b128 v[146:149], v17 offset:3072
	v_add_u32_e32 v17, 0x14000, v237
	ds_read_b128 v[150:153], v17
	ds_read_b128 v[154:157], v17 offset:1024
	ds_read_b128 v[158:161], v17 offset:2048
	ds_read_b128 v[162:165], v17 offset:3072
	ds_read_b128 v[166:169], v240
	ds_read_b128 v[186:189], v240 offset:1024
	ds_read_b128 v[190:193], v240 offset:2048
	ds_read_b128 v[194:197], v240 offset:3072
	ds_read_b128 v[198:201], v240 offset:4096
	ds_read_b128 v[202:205], v240 offset:5120
	ds_read_b128 v[206:209], v240 offset:6144
	ds_read_b128 v[210:213], v240 offset:7168
	s_add_i32 s4, s2, 2
	s_add_u32 s5, s68, s0
	s_addc_u32 s3, s69, s1
	s_add_u32 s33, s86, s0
	s_addc_u32 s35, s87, s1
	s_add_i32 s47, 0, 0x10000
	s_cmp_eq_u32 s21, s2
	s_cselect_b32 s3, s65, s3
	s_cselect_b32 s2, s64, s5
	s_cselect_b32 s57, s67, s35
	s_cselect_b32 s56, s66, s33
	s_add_i32 s5, 0, 0x14000
	s_add_i32 m0, s37, 0xc000
	v_lshl_add_u64 v[170:171], s[68:69], 0, v[132:133]
	global_load_lds_dwordx4 v[170:171], off
	v_lshl_add_u64 v[170:171], s[68:69], 0, v[18:19]
	s_add_i32 m0, s37, 0xe000
	s_nop 0
	global_load_lds_dwordx4 v[170:171], off
	s_waitcnt vmcnt(8)
	s_waitcnt lgkmcnt(0)
	s_setprio 1
	s_barrier
	v_mfma_f32_16x16x32_bf16 v[8:11], v[134:137], v[166:169], v[8:11]
	v_mfma_f32_16x16x32_bf16 v[12:15], v[142:145], v[166:169], v[12:15]
	v_mfma_f32_16x16x32_bf16 v[28:31], v[134:137], v[190:193], v[28:31]
	v_mfma_f32_16x16x32_bf16 v[32:35], v[142:145], v[190:193], v[32:35]
	v_mfma_f32_16x16x32_bf16 v[36:39], v[134:137], v[198:201], v[36:39]
	v_mfma_f32_16x16x32_bf16 v[44:47], v[142:145], v[198:201], v[44:47]
	v_mfma_f32_16x16x32_bf16 v[80:83], v[134:137], v[206:209], v[80:83]
	v_mfma_f32_16x16x32_bf16 v[88:91], v[142:145], v[206:209], v[88:91]
	v_mfma_f32_16x16x32_bf16 v[8:11], v[138:141], v[186:189], v[8:11]
	v_mfma_f32_16x16x32_bf16 v[12:15], v[146:149], v[186:189], v[12:15]
	v_mfma_f32_16x16x32_bf16 v[28:31], v[138:141], v[194:197], v[28:31]
	v_mfma_f32_16x16x32_bf16 v[32:35], v[146:149], v[194:197], v[32:35]
	v_mfma_f32_16x16x32_bf16 v[36:39], v[138:141], v[202:205], v[36:39]
	v_mfma_f32_16x16x32_bf16 v[44:47], v[146:149], v[202:205], v[44:47]
	v_mfma_f32_16x16x32_bf16 v[80:83], v[138:141], v[210:213], v[80:83]
	v_mfma_f32_16x16x32_bf16 v[88:91], v[146:149], v[210:213], v[88:91]
	v_mfma_f32_16x16x32_bf16 v[0:3], v[150:153], v[166:169], v[0:3]
	v_mfma_f32_16x16x32_bf16 v[4:7], v[158:161], v[166:169], v[4:7]
	v_mfma_f32_16x16x32_bf16 v[20:23], v[150:153], v[190:193], v[20:23]
	v_mfma_f32_16x16x32_bf16 v[24:27], v[158:161], v[190:193], v[24:27]
	v_mfma_f32_16x16x32_bf16 v[40:43], v[150:153], v[198:201], v[40:43]
	v_mfma_f32_16x16x32_bf16 v[48:51], v[158:161], v[198:201], v[48:51]
	v_mfma_f32_16x16x32_bf16 v[60:63], v[150:153], v[206:209], v[60:63]
	v_mfma_f32_16x16x32_bf16 v[64:67], v[158:161], v[206:209], v[64:67]
	v_mfma_f32_16x16x32_bf16 v[0:3], v[154:157], v[186:189], v[0:3]
	v_mfma_f32_16x16x32_bf16 v[4:7], v[162:165], v[186:189], v[4:7]
	v_mfma_f32_16x16x32_bf16 v[20:23], v[154:157], v[194:197], v[20:23]
	v_mfma_f32_16x16x32_bf16 v[24:27], v[162:165], v[194:197], v[24:27]
	v_mfma_f32_16x16x32_bf16 v[40:43], v[154:157], v[202:205], v[40:43]
	v_mfma_f32_16x16x32_bf16 v[48:51], v[162:165], v[202:205], v[48:51]
	v_mfma_f32_16x16x32_bf16 v[60:63], v[154:157], v[210:213], v[60:63]
	v_mfma_f32_16x16x32_bf16 v[64:67], v[162:165], v[210:213], v[64:67]
	s_barrier
	s_setprio 0
	ds_read_b128 v[166:169], v240 offset:16384
	ds_read_b128 v[186:189], v240 offset:17408
	ds_read_b128 v[190:193], v240 offset:18432
	ds_read_b128 v[194:197], v240 offset:19456
	ds_read_b128 v[198:201], v240 offset:20480
	ds_read_b128 v[202:205], v240 offset:21504
	ds_read_b128 v[206:209], v240 offset:22528
	ds_read_b128 v[210:213], v240 offset:23552
	s_add_i32 s33, s47, s17
	s_mov_b32 m0, s33
	v_lshl_add_u64 v[170:171], s[56:57], 0, v[174:175]
	global_load_lds_dwordx4 v[170:171], off
	s_add_i32 m0, s33, 0x2000
	v_lshl_add_u64 v[214:215], s[56:57], 0, v[178:179]
	s_add_u32 s56, s56, s36
	s_addc_u32 s57, s57, 0
	s_add_i32 s5, s5, s17
	global_load_lds_dwordx4 v[214:215], off
	v_lshl_add_u64 v[216:217], s[56:57], 0, v[174:175]
	s_mov_b32 m0, s5
	v_lshl_add_u64 v[224:225], s[56:57], 0, v[178:179]
	global_load_lds_dwordx4 v[216:217], off
	s_add_i32 m0, s5, 0x2000
	v_lshl_add_u64 v[226:227], s[2:3], 0, v[172:173]
	global_load_lds_dwordx4 v[224:225], off
	s_mov_b32 m0, s37
	v_lshl_add_u64 v[242:243], s[2:3], 0, v[176:177]
	global_load_lds_dwordx4 v[226:227], off
	s_mov_b32 m0, s45
	s_nop 0
	global_load_lds_dwordx4 v[242:243], off
	s_waitcnt vmcnt(8)
	s_waitcnt lgkmcnt(0)
	s_setprio 1
	s_barrier
	v_mfma_f32_16x16x32_bf16 v[68:71], v[134:137], v[166:169], v[68:71]
	v_mfma_f32_16x16x32_bf16 v[72:75], v[142:145], v[166:169], v[72:75]
	v_mfma_f32_16x16x32_bf16 v[92:95], v[134:137], v[190:193], v[92:95]
	v_mfma_f32_16x16x32_bf16 v[96:99], v[142:145], v[190:193], v[96:99]
	v_mfma_f32_16x16x32_bf16 v[108:111], v[134:137], v[198:201], v[108:111]
	v_mfma_f32_16x16x32_bf16 v[112:115], v[142:145], v[198:201], v[112:115]
	v_mfma_f32_16x16x32_bf16 v[124:127], v[134:137], v[206:209], v[124:127]
	v_mfma_f32_16x16x32_bf16 v[128:131], v[142:145], v[206:209], v[128:131]
	v_mfma_f32_16x16x32_bf16 v[68:71], v[138:141], v[186:189], v[68:71]
	v_mfma_f32_16x16x32_bf16 v[72:75], v[146:149], v[186:189], v[72:75]
	v_mfma_f32_16x16x32_bf16 v[92:95], v[138:141], v[194:197], v[92:95]
	v_mfma_f32_16x16x32_bf16 v[96:99], v[146:149], v[194:197], v[96:99]
	v_mfma_f32_16x16x32_bf16 v[108:111], v[138:141], v[202:205], v[108:111]
	v_mfma_f32_16x16x32_bf16 v[112:115], v[146:149], v[202:205], v[112:115]
	v_mfma_f32_16x16x32_bf16 v[124:127], v[138:141], v[210:213], v[124:127]
	v_mfma_f32_16x16x32_bf16 v[128:131], v[146:149], v[210:213], v[128:131]
	v_mfma_f32_16x16x32_bf16 v[52:55], v[150:153], v[166:169], v[52:55]
	v_mfma_f32_16x16x32_bf16 v[56:59], v[158:161], v[166:169], v[56:59]
	v_mfma_f32_16x16x32_bf16 v[76:79], v[150:153], v[190:193], v[76:79]
	v_mfma_f32_16x16x32_bf16 v[84:87], v[158:161], v[190:193], v[84:87]
	v_mfma_f32_16x16x32_bf16 v[100:103], v[150:153], v[198:201], v[100:103]
	v_mfma_f32_16x16x32_bf16 v[104:107], v[158:161], v[198:201], v[104:107]
	v_mfma_f32_16x16x32_bf16 v[116:119], v[150:153], v[206:209], v[116:119]
	v_mfma_f32_16x16x32_bf16 v[120:123], v[158:161], v[206:209], v[120:123]
	v_mfma_f32_16x16x32_bf16 v[52:55], v[154:157], v[186:189], v[52:55]
	v_mfma_f32_16x16x32_bf16 v[56:59], v[162:165], v[186:189], v[56:59]
	v_mfma_f32_16x16x32_bf16 v[76:79], v[154:157], v[194:197], v[76:79]
	v_mfma_f32_16x16x32_bf16 v[84:87], v[162:165], v[194:197], v[84:87]
	v_mfma_f32_16x16x32_bf16 v[100:103], v[154:157], v[202:205], v[100:103]
	v_mfma_f32_16x16x32_bf16 v[104:107], v[162:165], v[202:205], v[104:107]
	v_mfma_f32_16x16x32_bf16 v[116:119], v[154:157], v[210:213], v[116:119]
	v_mfma_f32_16x16x32_bf16 v[120:123], v[162:165], v[210:213], v[120:123]
	s_barrier
	s_setprio 0
	v_add_u32_e32 v17, 0x18000, v237
	ds_read_b128 v[134:137], v17
	ds_read_b128 v[138:141], v17 offset:1024
	ds_read_b128 v[142:145], v17 offset:2048
	ds_read_b128 v[146:149], v17 offset:3072
	v_add_u32_e32 v17, 0x1c000, v237
	ds_read_b128 v[150:153], v17
	ds_read_b128 v[154:157], v17 offset:1024
	ds_read_b128 v[158:161], v17 offset:2048
	ds_read_b128 v[162:165], v17 offset:3072
	ds_read_b128 v[166:169], v240 offset:32768
	ds_read_b128 v[186:189], v240 offset:33792
	ds_read_b128 v[190:193], v240 offset:34816
	ds_read_b128 v[194:197], v240 offset:35840
	ds_read_b128 v[198:201], v240 offset:36864
	ds_read_b128 v[202:205], v240 offset:37888
	ds_read_b128 v[206:209], v240 offset:38912
	ds_read_b128 v[210:213], v240 offset:39936
	s_add_i32 s5, 0, 0x18000
	s_add_i32 s33, 0, 0x1c000
	s_add_u32 s2, s2, s36
	s_addc_u32 s3, s3, 0
	s_mov_b32 m0, s26
	v_lshl_add_u64 v[244:245], s[2:3], 0, v[172:173]
	global_load_lds_dwordx4 v[244:245], off
	v_lshl_add_u64 v[244:245], s[2:3], 0, v[176:177]
	s_mov_b32 m0, s27
	s_nop 0
	global_load_lds_dwordx4 v[244:245], off
	s_waitcnt vmcnt(8)
	s_waitcnt lgkmcnt(0)
	s_setprio 1
	s_barrier
	v_mfma_f32_16x16x32_bf16 v[8:11], v[134:137], v[166:169], v[8:11]
	v_mfma_f32_16x16x32_bf16 v[12:15], v[142:145], v[166:169], v[12:15]
	v_mfma_f32_16x16x32_bf16 v[28:31], v[134:137], v[190:193], v[28:31]
	v_mfma_f32_16x16x32_bf16 v[32:35], v[142:145], v[190:193], v[32:35]
	v_mfma_f32_16x16x32_bf16 v[36:39], v[134:137], v[198:201], v[36:39]
	v_mfma_f32_16x16x32_bf16 v[44:47], v[142:145], v[198:201], v[44:47]
	v_mfma_f32_16x16x32_bf16 v[80:83], v[134:137], v[206:209], v[80:83]
	v_mfma_f32_16x16x32_bf16 v[88:91], v[142:145], v[206:209], v[88:91]
	v_mfma_f32_16x16x32_bf16 v[8:11], v[138:141], v[186:189], v[8:11]
	v_mfma_f32_16x16x32_bf16 v[12:15], v[146:149], v[186:189], v[12:15]
	v_mfma_f32_16x16x32_bf16 v[28:31], v[138:141], v[194:197], v[28:31]
	v_mfma_f32_16x16x32_bf16 v[32:35], v[146:149], v[194:197], v[32:35]
	v_mfma_f32_16x16x32_bf16 v[36:39], v[138:141], v[202:205], v[36:39]
	v_mfma_f32_16x16x32_bf16 v[44:47], v[146:149], v[202:205], v[44:47]
	v_mfma_f32_16x16x32_bf16 v[80:83], v[138:141], v[210:213], v[80:83]
	v_mfma_f32_16x16x32_bf16 v[88:91], v[146:149], v[210:213], v[88:91]
	v_mfma_f32_16x16x32_bf16 v[0:3], v[150:153], v[166:169], v[0:3]
	v_mfma_f32_16x16x32_bf16 v[4:7], v[158:161], v[166:169], v[4:7]
	v_mfma_f32_16x16x32_bf16 v[20:23], v[150:153], v[190:193], v[20:23]
	v_mfma_f32_16x16x32_bf16 v[24:27], v[158:161], v[190:193], v[24:27]
	v_mfma_f32_16x16x32_bf16 v[40:43], v[150:153], v[198:201], v[40:43]
	v_mfma_f32_16x16x32_bf16 v[48:51], v[158:161], v[198:201], v[48:51]
	v_mfma_f32_16x16x32_bf16 v[60:63], v[150:153], v[206:209], v[60:63]
	v_mfma_f32_16x16x32_bf16 v[64:67], v[158:161], v[206:209], v[64:67]
	v_mfma_f32_16x16x32_bf16 v[0:3], v[154:157], v[186:189], v[0:3]
	v_mfma_f32_16x16x32_bf16 v[4:7], v[162:165], v[186:189], v[4:7]
	v_mfma_f32_16x16x32_bf16 v[20:23], v[154:157], v[194:197], v[20:23]
	v_mfma_f32_16x16x32_bf16 v[24:27], v[162:165], v[194:197], v[24:27]
	v_mfma_f32_16x16x32_bf16 v[40:43], v[154:157], v[202:205], v[40:43]
	v_mfma_f32_16x16x32_bf16 v[48:51], v[162:165], v[202:205], v[48:51]
	v_mfma_f32_16x16x32_bf16 v[60:63], v[154:157], v[210:213], v[60:63]
	v_mfma_f32_16x16x32_bf16 v[64:67], v[162:165], v[210:213], v[64:67]
	s_barrier
	s_setprio 0
	ds_read_b128 v[166:169], v240 offset:49152
	ds_read_b128 v[186:189], v240 offset:50176
	ds_read_b128 v[190:193], v240 offset:51200
	ds_read_b128 v[194:197], v240 offset:52224
	ds_read_b128 v[198:201], v240 offset:53248
	ds_read_b128 v[202:205], v240 offset:54272
	ds_read_b128 v[206:209], v240 offset:55296
	ds_read_b128 v[210:213], v240 offset:56320
	s_add_i32 s2, s5, s17
	s_mov_b32 m0, s2
	v_lshl_add_u64 v[170:171], v[170:171], 0, s[6:7]
	global_load_lds_dwordx4 v[170:171], off
	v_lshl_add_u64 v[170:171], v[214:215], 0, s[6:7]
	s_add_i32 m0, s2, 0x2000
	s_add_i32 s2, s33, s17
	global_load_lds_dwordx4 v[170:171], off
	v_lshl_add_u64 v[170:171], v[216:217], 0, s[6:7]
	s_mov_b32 m0, s2
	s_nop 0
	global_load_lds_dwordx4 v[170:171], off
	v_lshl_add_u64 v[170:171], v[224:225], 0, s[6:7]
	s_add_i32 m0, s2, 0x2000
	s_nop 0
	global_load_lds_dwordx4 v[170:171], off
	v_lshl_add_u64 v[170:171], v[226:227], 0, s[6:7]
	s_mov_b32 m0, s63
	s_nop 0
	global_load_lds_dwordx4 v[170:171], off
	v_lshl_add_u64 v[170:171], v[242:243], 0, s[6:7]
	s_mov_b32 m0, s20
	s_nop 0
	global_load_lds_dwordx4 v[170:171], off
	s_waitcnt vmcnt(8)
	s_waitcnt lgkmcnt(0)
	s_setprio 1
	s_barrier
	v_mfma_f32_16x16x32_bf16 v[68:71], v[134:137], v[166:169], v[68:71]
	v_mfma_f32_16x16x32_bf16 v[72:75], v[142:145], v[166:169], v[72:75]
	v_mfma_f32_16x16x32_bf16 v[92:95], v[134:137], v[190:193], v[92:95]
	v_mfma_f32_16x16x32_bf16 v[96:99], v[142:145], v[190:193], v[96:99]
	v_mfma_f32_16x16x32_bf16 v[108:111], v[134:137], v[198:201], v[108:111]
	v_mfma_f32_16x16x32_bf16 v[112:115], v[142:145], v[198:201], v[112:115]
	v_mfma_f32_16x16x32_bf16 v[124:127], v[134:137], v[206:209], v[124:127]
	v_mfma_f32_16x16x32_bf16 v[128:131], v[142:145], v[206:209], v[128:131]
	v_mfma_f32_16x16x32_bf16 v[68:71], v[138:141], v[186:189], v[68:71]
	v_mfma_f32_16x16x32_bf16 v[72:75], v[146:149], v[186:189], v[72:75]
	v_mfma_f32_16x16x32_bf16 v[92:95], v[138:141], v[194:197], v[92:95]
	v_mfma_f32_16x16x32_bf16 v[96:99], v[146:149], v[194:197], v[96:99]
	v_mfma_f32_16x16x32_bf16 v[108:111], v[138:141], v[202:205], v[108:111]
	v_mfma_f32_16x16x32_bf16 v[112:115], v[146:149], v[202:205], v[112:115]
	v_mfma_f32_16x16x32_bf16 v[124:127], v[138:141], v[210:213], v[124:127]
	v_mfma_f32_16x16x32_bf16 v[128:131], v[146:149], v[210:213], v[128:131]
	v_mfma_f32_16x16x32_bf16 v[52:55], v[150:153], v[166:169], v[52:55]
	v_mfma_f32_16x16x32_bf16 v[56:59], v[158:161], v[166:169], v[56:59]
	v_mfma_f32_16x16x32_bf16 v[76:79], v[150:153], v[190:193], v[76:79]
	v_mfma_f32_16x16x32_bf16 v[84:87], v[158:161], v[190:193], v[84:87]
	v_mfma_f32_16x16x32_bf16 v[100:103], v[150:153], v[198:201], v[100:103]
	v_mfma_f32_16x16x32_bf16 v[104:107], v[158:161], v[198:201], v[104:107]
	v_mfma_f32_16x16x32_bf16 v[116:119], v[150:153], v[206:209], v[116:119]
	v_mfma_f32_16x16x32_bf16 v[120:123], v[158:161], v[206:209], v[120:123]
	v_mfma_f32_16x16x32_bf16 v[52:55], v[154:157], v[186:189], v[52:55]
	v_mfma_f32_16x16x32_bf16 v[56:59], v[162:165], v[186:189], v[56:59]
	v_mfma_f32_16x16x32_bf16 v[76:79], v[154:157], v[194:197], v[76:79]
	v_mfma_f32_16x16x32_bf16 v[84:87], v[162:165], v[194:197], v[84:87]
	v_mfma_f32_16x16x32_bf16 v[100:103], v[154:157], v[202:205], v[100:103]
	v_mfma_f32_16x16x32_bf16 v[104:107], v[162:165], v[202:205], v[104:107]
	v_mfma_f32_16x16x32_bf16 v[116:119], v[154:157], v[210:213], v[116:119]
	v_mfma_f32_16x16x32_bf16 v[120:123], v[162:165], v[210:213], v[120:123]
	s_barrier
	s_setprio 0
	s_add_u32 s0, s0, 0x100
	s_addc_u32 s1, s1, 0
	v_lshl_add_u64 v[132:133], v[132:133], 0, s[8:9]
	v_lshl_add_u64 v[18:19], v[18:19], 0, s[8:9]
	s_cmp_ge_u32 s4, s62
	s_mov_b32 s2, s4
	s_cbranch_scc0 .LBB0_344
	v_readlane_b32 s0, v253, 40
	v_readlane_b32 s1, v253, 41
	s_and_b64 vcc, exec, s[0:1]
	s_cbranch_vccz .LBB0_347
	s_barrier
